# first-consumer counted waits in gates/in1 epilogue heads plus removal of 10 non-hazard s_nop pads in the Gates epilogue
# speedup vs baseline: 1.0091x; 1.0076x over previous
; template <int NP> __device__ __forceinline__ void row_scales(float (&rs)[2][4], const float* base, long row0, int fq, float inv_n) {
;     float t[2][4];
; #pragma unroll
;     for (int ai = 0; ai < 2; ++ai)
; #pragma unroll
;         for (int m = 0; m < 4; ++m) { const long row = row0 + ai * 128 + m * 16;
;             if (NP == 16) { const f32x4 v = *(const f32x4*)(base + row * 16 + 4 * fq); t[ai][m] = (v.x + v.y) + (v.z + v.w); }
;             else if (NP == 8) { const f32x2 v = *(const f32x2*)(base + row * 8 + 2 * fq); t[ai][m] = v.x + v.y; }
;             else t[ai][m] = base[row * 4 + fq]; }
; #pragma unroll
;     for (int ai = 0; ai < 2; ++ai)
; #pragma unroll
;         for (int m = 0; m < 4; ++m) rs[ai][m] = rsqrtf(red_fq(t[ai][m]) * inv_n + EPS);
; }
;     __device__ __forceinline__ void operator()(AccT& acc, const Unit& u, int wr, int wc, int fr, int fq, LAS unsigned char*) const {
;         const long row0 = (long)u.pm * 256 + wr * 64 + fr;
;         const size_t tb = ((size_t)(u.pm * 12 + u.pn) * 8 + (wr * 4 + wc)) * 16; const int lane = fq * 16 + fr;
;         float rsa[2][4]; row_scales<16>(rsa, ssqx, row0, fq, 1.f / 1024.f);
.LBB0_335:
	s_ashr_i32 s1, s0, 31
	s_mul_i32 s8, s0, 12
	s_lshl_b64 s[0:1], s[0:1], 14
	v_lshl_add_u64 v[144:145], v[134:135], 0, s[0:1]
	global_load_dwordx4 v[140:143], v[144:145], off
	s_add_i32 s8, s8, s79
	s_ashr_i32 s9, s8, 31
	s_lshl_b64 s[12:13], s[8:9], 17
	s_movk_i32 s8, 0x2000
	v_add_co_u32_e32 v162, vcc, s8, v144
	s_mov_b32 s0, 0x358637bd
	s_nop 0
	v_addc_co_u32_e32 v163, vcc, 0, v145, vcc
	global_load_dwordx4 v[156:159], v[162:163], off offset:2048
	global_load_dwordx4 v[164:167], v[144:145], off offset:1024
	global_load_dwordx4 v[168:171], v[144:145], off offset:2048
	global_load_dwordx4 v[172:175], v[144:145], off offset:3072
	global_load_dwordx4 v[176:179], v[162:163], off
	global_load_dwordx4 v[180:183], v[162:163], off offset:1024
	global_load_dwordx4 v[184:187], v[162:163], off offset:3072
	s_mov_b32 s18, 0x3a800000
	s_movk_i32 s75, 0xc0
	s_mov_b32 s26, 0x18000
	s_waitcnt vmcnt(7)
	v_mov_b32_e32 v146, v141
	v_mov_b32_e32 v147, v142
	v_mov_b32_e32 v141, v143
	v_pk_add_f32 v[140:141], v[146:147], v[140:141]
	s_nop 0
	v_pk_add_f32 v[150:151], v[140:141], v[140:141] op_sel:[0,1] op_sel_hi:[1,0]
	s_waitcnt vmcnt(5)
	v_mov_b64_e32 v[140:141], v[164:165]
	v_mov_b64_e32 v[142:143], v[166:167]
	v_mov_b32_e32 v146, v141
	v_mov_b32_e32 v147, v142
	v_mov_b32_e32 v141, v143
	v_pk_add_f32 v[140:141], v[146:147], v[140:141]
	s_nop 0
	v_pk_add_f32 v[160:161], v[140:141], v[140:141] op_sel:[0,1] op_sel_hi:[1,0]
	s_waitcnt vmcnt(4)
	v_mov_b64_e32 v[140:141], v[168:169]
	v_mov_b64_e32 v[142:143], v[170:171]
	v_mov_b32_e32 v146, v141
	v_mov_b32_e32 v147, v142
	v_mov_b32_e32 v141, v143
	v_pk_add_f32 v[140:141], v[146:147], v[140:141]
	s_nop 0
	v_pk_add_f32 v[152:153], v[140:141], v[140:141] op_sel:[0,1] op_sel_hi:[1,0]
	s_waitcnt vmcnt(3)
	v_mov_b64_e32 v[140:141], v[172:173]
	v_mov_b64_e32 v[142:143], v[174:175]
	v_mov_b32_e32 v146, v141
	v_mov_b32_e32 v147, v142
	v_mov_b32_e32 v141, v143
	v_pk_add_f32 v[140:141], v[146:147], v[140:141]
	s_nop 0
	v_pk_add_f32 v[148:149], v[140:141], v[140:141] op_sel:[0,1] op_sel_hi:[1,0]
	s_waitcnt vmcnt(2)
	v_mov_b64_e32 v[140:141], v[176:177]
	v_mov_b64_e32 v[142:143], v[178:179]
	v_mov_b32_e32 v144, v141
	v_mov_b32_e32 v145, v142
	v_mov_b32_e32 v141, v143
	v_pk_add_f32 v[140:141], v[144:145], v[140:141]
	s_waitcnt vmcnt(1)
	v_mov_b64_e32 v[144:145], v[180:181]
	v_mov_b64_e32 v[146:147], v[182:183]
	v_pk_add_f32 v[142:143], v[140:141], v[140:141] op_sel:[0,1] op_sel_hi:[1,0]
	v_mov_b32_e32 v140, v145
	v_mov_b32_e32 v141, v146
	v_mov_b32_e32 v145, v147
	v_pk_add_f32 v[140:141], v[140:141], v[144:145]
	s_nop 0
	v_pk_add_f32 v[146:147], v[140:141], v[140:141] op_sel:[0,1] op_sel_hi:[1,0]
	v_mov_b32_e32 v140, v157
	v_mov_b32_e32 v141, v158
	v_mov_b32_e32 v157, v159
	v_pk_add_f32 v[140:141], v[140:141], v[156:157]
	s_waitcnt vmcnt(0)
	v_mov_b64_e32 v[156:157], v[184:185]
	v_mov_b64_e32 v[158:159], v[186:187]
	v_pk_add_f32 v[140:141], v[140:141], v[140:141] op_sel:[0,1] op_sel_hi:[1,0]
	v_mov_b32_e32 v144, v157
	v_mov_b32_e32 v141, v150
	s_nop 1
	v_permlane16_swap_b32_e32 v150, v141
	v_add_f32_e32 v151, v150, v141
	v_mov_b32_e32 v141, v160
	s_nop 1
	v_permlane16_swap_b32_e32 v160, v141
	v_mov_b32_e32 v145, v158
	v_mov_b32_e32 v157, v159
	v_add_f32_e32 v150, v160, v141
	v_pk_add_f32 v[144:145], v[144:145], v[156:157]
	v_mov_b32_e32 v157, v151
	v_mov_b32_e32 v156, v150
	s_nop 0
	v_permlane32_swap_b32_e32 v151, v157
	v_permlane32_swap_b32_e32 v150, v156
	v_pk_add_f32 v[156:157], v[150:151], v[156:157]
	v_mov_b64_e32 v[150:151], s[0:1]
	v_pk_fma_f32 v[156:157], v[156:157], s[18:19], v[150:151] op_sel_hi:[1,0,0]
	v_pk_add_f32 v[144:145], v[144:145], v[144:145] op_sel:[0,1] op_sel_hi:[1,0]
	v_mul_f32_e32 v141, 0x4b800000, v157
	v_cmp_gt_f32_e64 s[0:1], s33, v157
	v_cmp_gt_f32_e32 vcc, s33, v156
	s_nop 0
	v_cndmask_b32_e64 v141, v157, v141, s[0:1]
	v_rsq_f32_e32 v141, v141
	s_nop 0
	v_mul_f32_e32 v143, 0x45800000, v141
	v_cndmask_b32_e64 v149, v141, v143, s[0:1]
	v_mul_f32_e32 v141, 0x4b800000, v156
	v_cndmask_b32_e32 v141, v156, v141, vcc
	v_rsq_f32_e32 v141, v141
	s_nop 0
	v_mul_f32_e32 v143, 0x45800000, v141
	v_cndmask_b32_e32 v147, v141, v143, vcc
	v_mov_b32_e32 v141, v152
	s_nop 1
	v_permlane16_swap_b32_e32 v152, v141
	v_add_f32_e32 v153, v152, v141
	v_mov_b32_e32 v141, v148
	s_nop 1
	v_permlane16_swap_b32_e32 v148, v141
	v_add_f32_e32 v152, v148, v141
	v_mov_b32_e32 v157, v153
	v_mov_b32_e32 v156, v152
	s_nop 0
	v_permlane32_swap_b32_e32 v153, v157
	v_permlane32_swap_b32_e32 v152, v156
	v_pk_add_f32 v[152:153], v[152:153], v[156:157]
	s_nop 0
	v_pk_fma_f32 v[152:153], v[152:153], s[18:19], v[150:151] op_sel_hi:[1,0,0]
	s_nop 0
	v_mul_f32_e32 v141, 0x4b800000, v153
	v_cmp_gt_f32_e64 s[0:1], s33, v153
	v_cmp_gt_f32_e32 vcc, s33, v152
	s_nop 0
	v_cndmask_b32_e64 v141, v153, v141, s[0:1]
	v_rsq_f32_e32 v141, v141
	s_nop 0
	v_mul_f32_e32 v143, 0x45800000, v141
	v_cndmask_b32_e64 v148, v141, v143, s[0:1]
	v_mul_f32_e32 v141, 0x4b800000, v152
	v_cndmask_b32_e32 v141, v152, v141, vcc
	v_rsq_f32_e32 v141, v141
	s_nop 0
	v_mul_f32_e32 v143, 0x45800000, v141
	v_cndmask_b32_e32 v145, v141, v143, vcc
	v_mov_b32_e32 v141, v142
	s_nop 1
	v_permlane16_swap_b32_e32 v142, v141
	v_add_f32_e32 v143, v142, v141
	v_mov_b32_e32 v141, v146
	s_nop 1
	v_permlane16_swap_b32_e32 v146, v141
	v_add_f32_e32 v142, v146, v141
	v_mov_b32_e32 v153, v143
	v_mov_b32_e32 v152, v142
	s_nop 0
	v_permlane32_swap_b32_e32 v143, v153
	v_permlane32_swap_b32_e32 v142, v152
	v_pk_add_f32 v[142:143], v[142:143], v[152:153]
	s_nop 0
	v_pk_fma_f32 v[142:143], v[142:143], s[18:19], v[150:151] op_sel_hi:[1,0,0]
	s_nop 0
	v_mul_f32_e32 v141, 0x4b800000, v143
; __device__ __forceinline__ unsigned pk2(float lo, float hi) { f32x2 v = {lo, hi}; bf16x2_t b = __builtin_convertvector(v, bf16x2_t); return __builtin_bit_cast(unsigned, b); }
; #define SG_(t) __builtin_amdgcn_rcpf(1.f + __builtin_amdgcn_exp2f(min2f(t, 19.931568f)))
; template <int NP> __device__ __forceinline__ void row_scales(float (&rs)[2][4], const float* base, long row0, int fq, float inv_n) {
;     ...
;         for (int m = 0; m < 4; ++m) rs[ai][m] = rsqrtf(red_fq(t[ai][m]) * inv_n + EPS);
;     __device__ __forceinline__ void operator()(AccT& acc, const Unit& u, int wr, int wc, int fr, int fq, LAS unsigned char*) const {
;     ...
;             for (int m = 0; m < 4; ++m) {
;                 const float rs = rsa[ai][m] * -LOG2E;
;     ...
; #pragma unroll
;                 for (int bj = 0; bj < 2; ++bj) { const f32x4 v0 = acc[ai][bj][m][0] * rs, v1 = acc[ai][bj][m][1] * rs; u32x4 w;
;                     w.x = pk2(SG_(v0.x), SG_(v0.y)); w.y = pk2(SG_(v0.z), SG_(v0.w)); w.z = pk2(SG_(v1.x), SG_(v1.y)); w.w = pk2(SG_(v1.z), SG_(v1.w));
;     ...
;                     *(u32x4*)(gates + ((tb + (ai * 4 + m) * 2 + bj) * 64 + lane) * 8) = w; }
;             }
	v_cmp_gt_f32_e64 s[0:1], s33, v143
	v_cmp_gt_f32_e32 vcc, s33, v142
	s_nop 0
	v_cndmask_b32_e64 v141, v143, v141, s[0:1]
	v_rsq_f32_e32 v141, v141
	s_nop 0
	v_mul_f32_e32 v143, 0x45800000, v141
	v_cndmask_b32_e64 v143, v141, v143, s[0:1]
	v_mul_f32_e32 v141, 0x4b800000, v142
	v_cndmask_b32_e32 v141, v142, v141, vcc
	v_rsq_f32_e32 v141, v141
	s_nop 0
	v_mul_f32_e32 v142, 0x45800000, v141
	v_cndmask_b32_e32 v142, v141, v142, vcc
	v_mov_b32_e32 v141, v140
	s_nop 1
	v_permlane16_swap_b32_e32 v140, v141
	v_add_f32_e32 v141, v140, v141
	v_mov_b32_e32 v140, v144
	s_nop 1
	v_permlane16_swap_b32_e32 v144, v140
	v_add_f32_e32 v140, v144, v140
	v_mov_b32_e32 v153, v141
	v_mov_b32_e32 v152, v140
	s_nop 0
	v_permlane32_swap_b32_e32 v141, v153
	v_permlane32_swap_b32_e32 v140, v152
	v_pk_add_f32 v[140:141], v[140:141], v[152:153]
	s_nop 0
	v_pk_fma_f32 v[140:141], v[140:141], s[18:19], v[150:151] op_sel_hi:[1,0,0]
	s_nop 0
	v_mul_f32_e32 v144, 0x4b800000, v141
	v_cmp_gt_f32_e64 s[0:1], s33, v141
	v_cmp_gt_f32_e32 vcc, s33, v140
	s_nop 0
	v_cndmask_b32_e64 v141, v141, v144, s[0:1]
	v_rsq_f32_e32 v141, v141
	s_nop 0
	v_mul_f32_e32 v144, 0x45800000, v141
	v_cndmask_b32_e64 v141, v141, v144, s[0:1]
	v_mul_f32_e32 v144, 0x4b800000, v140
	v_cndmask_b32_e32 v140, v140, v144, vcc
	v_rsq_f32_e32 v140, v140
	s_add_u32 s0, s2, s12
	s_addc_u32 s1, s55, s13
	v_mul_f32_e32 v144, 0x45800000, v140
	v_cndmask_b32_e32 v140, v140, v144, vcc
	v_mul_f32_e32 v144, 0xbfb8aa3b, v149
	v_pk_mul_f32 v[126:127], v[126:127], v[144:145] op_sel_hi:[1,0]
	v_pk_mul_f32 v[150:151], v[124:125], v[144:145] op_sel_hi:[1,0]
	v_min_f32_e32 v124, v126, v246
	v_min_f32_e32 v125, v127, v246
	v_pk_mul_f32 v[122:123], v[122:123], v[144:145] op_sel_hi:[1,0]
	v_exp_f32_e32 v124, v124
	v_exp_f32_e32 v125, v125
	v_pk_mul_f32 v[128:129], v[128:129], v[144:145] op_sel_hi:[1,0]
	v_min_f32_e32 v122, v122, v246
	v_add_f32_e32 v124, 1.0, v124
	v_add_f32_e32 v125, 1.0, v125
	v_rcp_f32_e32 v124, v124
	v_rcp_f32_e32 v125, v125
	v_min_f32_e32 v126, v129, v246
	v_min_f32_e32 v123, v123, v246
	v_exp_f32_e32 v122, v122
	v_cvt_pk_bf16_f32 v124, v124, v125
	v_min_f32_e32 v125, v128, v246
	v_exp_f32_e32 v126, v126
	v_exp_f32_e32 v125, v125
	v_exp_f32_e32 v123, v123
	v_add_f32_e32 v122, 1.0, v122
	v_add_f32_e32 v126, 1.0, v126
	v_add_f32_e32 v125, 1.0, v125
	v_add_f32_e32 v123, 1.0, v123
	v_rcp_f32_e32 v125, v125
	v_rcp_f32_e32 v126, v126
	v_rcp_f32_e32 v122, v122
	v_rcp_f32_e32 v123, v123
	v_pk_mul_f32 v[118:119], v[118:119], v[144:145] op_sel_hi:[1,0]
	v_cvt_pk_bf16_f32 v125, v125, v126
	v_pk_mul_f32 v[120:121], v[120:121], v[144:145] op_sel_hi:[1,0]
	v_cvt_pk_bf16_f32 v126, v122, v123
	v_min_f32_e32 v122, v150, v246
	v_min_f32_e32 v123, v151, v246
	v_exp_f32_e32 v122, v122
	v_exp_f32_e32 v123, v123
	v_add_f32_e32 v122, 1.0, v122
	v_add_f32_e32 v123, 1.0, v123
	v_rcp_f32_e32 v122, v122
	v_rcp_f32_e32 v123, v123
	s_nop 0
	v_cvt_pk_bf16_f32 v127, v122, v123
	global_store_dwordx4 v0, v[124:127], s[0:1]
	v_lshl_add_u64 v[122:123], s[0:1], 0, v[0:1]
	s_nop 0
	v_pk_mul_f32 v[124:125], v[116:117], v[144:145] op_sel_hi:[1,0]
	v_pk_mul_f32 v[116:117], v[114:115], v[144:145] op_sel_hi:[1,0]
	v_min_f32_e32 v114, v118, v246
	v_min_f32_e32 v115, v119, v246
	v_min_f32_e32 v118, v121, v246
	v_exp_f32_e32 v114, v114
	v_exp_f32_e32 v115, v115
	v_min_f32_e32 v116, v116, v246
	v_min_f32_e32 v117, v117, v246
	v_add_f32_e32 v114, 1.0, v114
	v_add_f32_e32 v115, 1.0, v115
	v_rcp_f32_e32 v114, v114
	v_rcp_f32_e32 v115, v115
	v_exp_f32_e32 v118, v118
	v_exp_f32_e32 v116, v116
	v_exp_f32_e32 v117, v117
	v_cvt_pk_bf16_f32 v114, v114, v115
	v_min_f32_e32 v115, v120, v246
	v_add_f32_e32 v118, 1.0, v118
	v_exp_f32_e32 v115, v115
	v_add_f32_e32 v116, 1.0, v116
	v_add_f32_e32 v117, 1.0, v117
	v_rcp_f32_e32 v118, v118
	v_add_f32_e32 v115, 1.0, v115
	v_rcp_f32_e32 v115, v115
	v_rcp_f32_e32 v116, v116
	v_rcp_f32_e32 v117, v117
	v_cvt_pk_bf16_f32 v115, v115, v118
	v_min_f32_e32 v118, v125, v246
	v_cvt_pk_bf16_f32 v116, v116, v117
	v_min_f32_e32 v117, v124, v246
	v_exp_f32_e32 v118, v118
	v_exp_f32_e32 v117, v117
	v_add_f32_e32 v118, 1.0, v118
	v_add_f32_e32 v117, 1.0, v117
	v_rcp_f32_e32 v117, v117
	v_rcp_f32_e32 v118, v118
	s_nop 0
	v_cvt_pk_bf16_f32 v117, v117, v118
	global_store_dwordx4 v0, v[114:117], s[0:1] offset:1024
	s_nop 1
	v_mul_f32_e32 v114, 0xbfb8aa3b, v147
	v_pk_mul_f32 v[110:111], v[110:111], v[114:115] op_sel_hi:[1,0]
	v_pk_mul_f32 v[116:117], v[108:109], v[114:115] op_sel_hi:[1,0]
	v_pk_mul_f32 v[108:109], v[106:107], v[114:115] op_sel_hi:[1,0]
	v_min_f32_e32 v106, v110, v246
	v_min_f32_e32 v107, v111, v246
	v_pk_mul_f32 v[112:113], v[112:113], v[114:115] op_sel_hi:[1,0]
	v_exp_f32_e32 v106, v106
	v_exp_f32_e32 v107, v107
	v_min_f32_e32 v110, v113, v246
	v_min_f32_e32 v108, v108, v246
	v_add_f32_e32 v106, 1.0, v106
	v_add_f32_e32 v107, 1.0, v107
	v_rcp_f32_e32 v106, v106
	v_rcp_f32_e32 v107, v107
	v_min_f32_e32 v109, v109, v246
	v_exp_f32_e32 v110, v110
	v_exp_f32_e32 v108, v108
	v_cvt_pk_bf16_f32 v106, v106, v107
	v_min_f32_e32 v107, v112, v246
	v_exp_f32_e32 v109, v109
	v_exp_f32_e32 v107, v107
	v_add_f32_e32 v110, 1.0, v110
	v_add_f32_e32 v108, 1.0, v108
	v_add_f32_e32 v109, 1.0, v109
	v_add_f32_e32 v107, 1.0, v107
	v_rcp_f32_e32 v107, v107
	v_rcp_f32_e32 v110, v110
	v_rcp_f32_e32 v108, v108
	v_rcp_f32_e32 v109, v109
	v_pk_mul_f32 v[102:103], v[102:103], v[114:115] op_sel_hi:[1,0]
	v_cvt_pk_bf16_f32 v107, v107, v110
	v_min_f32_e32 v110, v117, v246
	v_cvt_pk_bf16_f32 v108, v108, v109
	v_min_f32_e32 v109, v116, v246
	v_exp_f32_e32 v110, v110
	v_exp_f32_e32 v109, v109
	v_pk_mul_f32 v[104:105], v[104:105], v[114:115] op_sel_hi:[1,0]
; __device__ __forceinline__ unsigned pk2(float lo, float hi) { f32x2 v = {lo, hi}; bf16x2_t b = __builtin_convertvector(v, bf16x2_t); return __builtin_bit_cast(unsigned, b); }
; #define SG_(t) __builtin_amdgcn_rcpf(1.f + __builtin_amdgcn_exp2f(min2f(t, 19.931568f)))
;     __device__ __forceinline__ void operator()(AccT& acc, const Unit& u, int wr, int wc, int fr, int fq, LAS unsigned char*) const {
;     ...
;             for (int m = 0; m < 4; ++m) {
;                 const float rs = rsa[ai][m] * -LOG2E;
;     ...
; #pragma unroll
;                 for (int bj = 0; bj < 2; ++bj) { const f32x4 v0 = acc[ai][bj][m][0] * rs, v1 = acc[ai][bj][m][1] * rs; u32x4 w;
;                     w.x = pk2(SG_(v0.x), SG_(v0.y)); w.y = pk2(SG_(v0.z), SG_(v0.w)); w.z = pk2(SG_(v1.x), SG_(v1.y)); w.w = pk2(SG_(v1.z), SG_(v1.w));
;     ...
;                     *(u32x4*)(gates + ((tb + (ai * 4 + m) * 2 + bj) * 64 + lane) * 8) = w; }
;             }
	v_add_f32_e32 v110, 1.0, v110
	v_add_f32_e32 v109, 1.0, v109
	v_rcp_f32_e32 v109, v109
	v_rcp_f32_e32 v110, v110
	s_nop 0
	v_cvt_pk_bf16_f32 v109, v109, v110
	global_store_dwordx4 v0, v[106:109], s[0:1] offset:2048
	s_nop 1
	v_pk_mul_f32 v[106:107], v[100:101], v[114:115] op_sel_hi:[1,0]
	v_pk_mul_f32 v[100:101], v[98:99], v[114:115] op_sel_hi:[1,0]
	v_min_f32_e32 v98, v102, v246
	v_min_f32_e32 v99, v103, v246
	v_min_f32_e32 v102, v105, v246
	v_exp_f32_e32 v98, v98
	v_exp_f32_e32 v99, v99
	v_min_f32_e32 v100, v100, v246
	v_min_f32_e32 v101, v101, v246
	v_add_f32_e32 v98, 1.0, v98
	v_add_f32_e32 v99, 1.0, v99
	v_rcp_f32_e32 v98, v98
	v_rcp_f32_e32 v99, v99
	v_exp_f32_e32 v102, v102
	v_exp_f32_e32 v100, v100
	v_exp_f32_e32 v101, v101
	v_cvt_pk_bf16_f32 v98, v98, v99
	v_min_f32_e32 v99, v104, v246
	v_add_f32_e32 v102, 1.0, v102
	v_exp_f32_e32 v99, v99
	v_add_f32_e32 v100, 1.0, v100
	v_add_f32_e32 v101, 1.0, v101
	v_rcp_f32_e32 v102, v102
	v_add_f32_e32 v99, 1.0, v99
	v_rcp_f32_e32 v99, v99
	v_rcp_f32_e32 v100, v100
	v_rcp_f32_e32 v101, v101
	v_cvt_pk_bf16_f32 v99, v99, v102
	v_min_f32_e32 v102, v107, v246
	v_cvt_pk_bf16_f32 v100, v100, v101
	v_min_f32_e32 v101, v106, v246
	v_exp_f32_e32 v102, v102
	v_exp_f32_e32 v101, v101
	v_add_f32_e32 v102, 1.0, v102
	v_add_f32_e32 v101, 1.0, v101
	v_rcp_f32_e32 v101, v101
	v_rcp_f32_e32 v102, v102
	s_nop 0
	v_cvt_pk_bf16_f32 v101, v101, v102
	global_store_dwordx4 v0, v[98:101], s[0:1] offset:3072
	s_movk_i32 s0, 0x1000
	s_nop 0
	v_mul_f32_e32 v98, 0xbfb8aa3b, v148
	v_pk_mul_f32 v[94:95], v[94:95], v[98:99] op_sel_hi:[1,0]
	v_pk_mul_f32 v[96:97], v[96:97], v[98:99] op_sel_hi:[1,0]
	v_min_f32_e32 v94, v94, v246
	v_min_f32_e32 v95, v95, v246
	v_pk_mul_f32 v[90:91], v[90:91], v[98:99] op_sel_hi:[1,0]
	v_exp_f32_e32 v94, v94
	v_exp_f32_e32 v95, v95
	v_min_f32_e32 v90, v90, v246
	v_min_f32_e32 v91, v91, v246
	v_add_f32_e32 v94, 1.0, v94
	v_add_f32_e32 v95, 1.0, v95
	v_rcp_f32_e32 v94, v94
	v_rcp_f32_e32 v95, v95
	v_exp_f32_e32 v90, v90
	v_exp_f32_e32 v91, v91
	v_pk_mul_f32 v[92:93], v[92:93], v[98:99] op_sel_hi:[1,0]
	v_cvt_pk_bf16_f32 v94, v94, v95
	v_min_f32_e32 v95, v96, v246
	v_min_f32_e32 v96, v97, v246
	v_add_f32_e32 v90, 1.0, v90
	v_exp_f32_e32 v95, v95
	v_exp_f32_e32 v96, v96
	v_add_f32_e32 v91, 1.0, v91
	v_rcp_f32_e32 v90, v90
	v_add_f32_e32 v95, 1.0, v95
	v_add_f32_e32 v96, 1.0, v96
	v_rcp_f32_e32 v95, v95
	v_rcp_f32_e32 v96, v96
	v_rcp_f32_e32 v91, v91
	v_pk_mul_f32 v[86:87], v[86:87], v[98:99] op_sel_hi:[1,0]
	v_pk_mul_f32 v[88:89], v[88:89], v[98:99] op_sel_hi:[1,0]
	v_cvt_pk_bf16_f32 v95, v95, v96
	v_cvt_pk_bf16_f32 v96, v90, v91
	v_min_f32_e32 v90, v92, v246
	v_min_f32_e32 v91, v93, v246
	v_add_co_u32_e32 v92, vcc, s0, v122
	v_exp_f32_e32 v90, v90
	v_exp_f32_e32 v91, v91
	v_addc_co_u32_e32 v93, vcc, 0, v123, vcc
	v_add_f32_e32 v90, 1.0, v90
	v_add_f32_e32 v91, 1.0, v91
	v_rcp_f32_e32 v90, v90
	v_rcp_f32_e32 v91, v91
	s_movk_i32 s0, 0x3000
	v_cvt_pk_bf16_f32 v97, v90, v91
	v_add_co_u32_e32 v90, vcc, s8, v122
	s_nop 1
	v_addc_co_u32_e32 v91, vcc, 0, v123, vcc
	global_store_dwordx4 v[90:91], v[94:97], off offset:-4096
	s_nop 1
	v_pk_mul_f32 v[94:95], v[84:85], v[98:99] op_sel_hi:[1,0]
	v_pk_mul_f32 v[84:85], v[82:83], v[98:99] op_sel_hi:[1,0]
	v_min_f32_e32 v82, v86, v246
	v_min_f32_e32 v83, v87, v246
	v_min_f32_e32 v86, v89, v246
	v_exp_f32_e32 v82, v82
	v_exp_f32_e32 v83, v83
	v_min_f32_e32 v84, v84, v246
	v_min_f32_e32 v85, v85, v246
	v_add_f32_e32 v82, 1.0, v82
	v_add_f32_e32 v83, 1.0, v83
	v_rcp_f32_e32 v82, v82
	v_rcp_f32_e32 v83, v83
	v_exp_f32_e32 v86, v86
	v_exp_f32_e32 v84, v84
	v_exp_f32_e32 v85, v85
	v_cvt_pk_bf16_f32 v82, v82, v83
	v_min_f32_e32 v83, v88, v246
	v_add_f32_e32 v86, 1.0, v86
	v_exp_f32_e32 v83, v83
	v_add_f32_e32 v84, 1.0, v84
	v_add_f32_e32 v85, 1.0, v85
	v_rcp_f32_e32 v86, v86
	v_add_f32_e32 v83, 1.0, v83
	v_rcp_f32_e32 v83, v83
	v_rcp_f32_e32 v84, v84
	v_rcp_f32_e32 v85, v85
	v_cvt_pk_bf16_f32 v83, v83, v86
	v_min_f32_e32 v86, v95, v246
	v_cvt_pk_bf16_f32 v84, v84, v85
	v_min_f32_e32 v85, v94, v246
	v_exp_f32_e32 v86, v86
	v_exp_f32_e32 v85, v85
	v_add_f32_e32 v86, 1.0, v86
	v_add_f32_e32 v85, 1.0, v85
	v_rcp_f32_e32 v85, v85
	v_rcp_f32_e32 v86, v86
	s_nop 0
	v_cvt_pk_bf16_f32 v85, v85, v86
	global_store_dwordx4 v[92:93], v[82:85], off offset:1024
	s_nop 1
	v_mul_f32_e32 v82, 0xbfb8aa3b, v145
	v_pk_mul_f32 v[78:79], v[78:79], v[82:83] op_sel_hi:[1,0]
	v_pk_mul_f32 v[84:85], v[76:77], v[82:83] op_sel_hi:[1,0]
	v_pk_mul_f32 v[76:77], v[74:75], v[82:83] op_sel_hi:[1,0]
	v_min_f32_e32 v74, v78, v246
	v_min_f32_e32 v75, v79, v246
	v_pk_mul_f32 v[80:81], v[80:81], v[82:83] op_sel_hi:[1,0]
	v_exp_f32_e32 v74, v74
	v_exp_f32_e32 v75, v75
	v_min_f32_e32 v78, v81, v246
	v_min_f32_e32 v76, v76, v246
	v_add_f32_e32 v74, 1.0, v74
	v_add_f32_e32 v75, 1.0, v75
	v_rcp_f32_e32 v74, v74
	v_rcp_f32_e32 v75, v75
	v_min_f32_e32 v77, v77, v246
	v_exp_f32_e32 v78, v78
	v_exp_f32_e32 v76, v76
	v_cvt_pk_bf16_f32 v74, v74, v75
	v_min_f32_e32 v75, v80, v246
	v_exp_f32_e32 v77, v77
	v_exp_f32_e32 v75, v75
	v_add_f32_e32 v78, 1.0, v78
	v_add_f32_e32 v76, 1.0, v76
	v_add_f32_e32 v77, 1.0, v77
	v_add_f32_e32 v75, 1.0, v75
	v_rcp_f32_e32 v75, v75
	v_rcp_f32_e32 v78, v78
	v_rcp_f32_e32 v76, v76
	v_rcp_f32_e32 v77, v77
	v_pk_mul_f32 v[70:71], v[70:71], v[82:83] op_sel_hi:[1,0]
	v_cvt_pk_bf16_f32 v75, v75, v78
	v_min_f32_e32 v78, v85, v246
	v_cvt_pk_bf16_f32 v76, v76, v77
	v_min_f32_e32 v77, v84, v246
	v_exp_f32_e32 v78, v78
	v_exp_f32_e32 v77, v77
	v_pk_mul_f32 v[72:73], v[72:73], v[82:83] op_sel_hi:[1,0]
	v_add_f32_e32 v78, 1.0, v78
	v_add_f32_e32 v77, 1.0, v77
	v_rcp_f32_e32 v77, v77
; __device__ __forceinline__ unsigned pk2(float lo, float hi) { f32x2 v = {lo, hi}; bf16x2_t b = __builtin_convertvector(v, bf16x2_t); return __builtin_bit_cast(unsigned, b); }
; #define SG_(t) __builtin_amdgcn_rcpf(1.f + __builtin_amdgcn_exp2f(min2f(t, 19.931568f)))
;     __device__ __forceinline__ void operator()(AccT& acc, const Unit& u, int wr, int wc, int fr, int fq, LAS unsigned char*) const {
;     ...
;             for (int m = 0; m < 4; ++m) {
;                 const float rs = rsa[ai][m] * -LOG2E;
;     ...
; #pragma unroll
;                 for (int bj = 0; bj < 2; ++bj) { const f32x4 v0 = acc[ai][bj][m][0] * rs, v1 = acc[ai][bj][m][1] * rs; u32x4 w;
;                     w.x = pk2(SG_(v0.x), SG_(v0.y)); w.y = pk2(SG_(v0.z), SG_(v0.w)); w.z = pk2(SG_(v1.x), SG_(v1.y)); w.w = pk2(SG_(v1.z), SG_(v1.w));
;     ...
;                     *(u32x4*)(gates + ((tb + (ai * 4 + m) * 2 + bj) * 64 + lane) * 8) = w; }
;             }
	v_rcp_f32_e32 v78, v78
	s_nop 0
	v_cvt_pk_bf16_f32 v77, v77, v78
	global_store_dwordx4 v[92:93], v[74:77], off offset:2048
	s_nop 1
	v_pk_mul_f32 v[74:75], v[68:69], v[82:83] op_sel_hi:[1,0]
	v_pk_mul_f32 v[68:69], v[66:67], v[82:83] op_sel_hi:[1,0]
	v_min_f32_e32 v66, v70, v246
	v_min_f32_e32 v67, v71, v246
	v_min_f32_e32 v70, v73, v246
	v_exp_f32_e32 v66, v66
	v_exp_f32_e32 v67, v67
	v_min_f32_e32 v68, v68, v246
	v_min_f32_e32 v69, v69, v246
	v_add_f32_e32 v66, 1.0, v66
	v_add_f32_e32 v67, 1.0, v67
	v_rcp_f32_e32 v66, v66
	v_rcp_f32_e32 v67, v67
	v_exp_f32_e32 v70, v70
	v_exp_f32_e32 v68, v68
	v_exp_f32_e32 v69, v69
	v_cvt_pk_bf16_f32 v66, v66, v67
	v_min_f32_e32 v67, v72, v246
	v_add_f32_e32 v70, 1.0, v70
	v_exp_f32_e32 v67, v67
	v_add_f32_e32 v68, 1.0, v68
	v_add_f32_e32 v69, 1.0, v69
	v_rcp_f32_e32 v70, v70
	v_add_f32_e32 v67, 1.0, v67
	v_rcp_f32_e32 v67, v67
	v_rcp_f32_e32 v68, v68
	v_rcp_f32_e32 v69, v69
	v_cvt_pk_bf16_f32 v67, v67, v70
	v_min_f32_e32 v70, v75, v246
	v_cvt_pk_bf16_f32 v68, v68, v69
	v_min_f32_e32 v69, v74, v246
	v_exp_f32_e32 v70, v70
	v_exp_f32_e32 v69, v69
	v_add_f32_e32 v70, 1.0, v70
	v_add_f32_e32 v69, 1.0, v69
	v_rcp_f32_e32 v69, v69
	v_rcp_f32_e32 v70, v70
	s_nop 0
	v_cvt_pk_bf16_f32 v69, v69, v70
	global_store_dwordx4 v[92:93], v[66:69], off offset:3072
	s_nop 1
	v_mul_f32_e32 v66, 0xbfb8aa3b, v143
	v_pk_mul_f32 v[62:63], v[62:63], v[66:67] op_sel_hi:[1,0]
	v_pk_mul_f32 v[68:69], v[60:61], v[66:67] op_sel_hi:[1,0]
	v_pk_mul_f32 v[60:61], v[58:59], v[66:67] op_sel_hi:[1,0]
	v_min_f32_e32 v58, v62, v246
	v_min_f32_e32 v59, v63, v246
	v_pk_mul_f32 v[64:65], v[64:65], v[66:67] op_sel_hi:[1,0]
	v_exp_f32_e32 v58, v58
	v_exp_f32_e32 v59, v59
	v_min_f32_e32 v62, v65, v246
	v_min_f32_e32 v60, v60, v246
	v_add_f32_e32 v58, 1.0, v58
	v_add_f32_e32 v59, 1.0, v59
	v_rcp_f32_e32 v58, v58
	v_rcp_f32_e32 v59, v59
	v_min_f32_e32 v61, v61, v246
	v_exp_f32_e32 v62, v62
	v_exp_f32_e32 v60, v60
	v_cvt_pk_bf16_f32 v58, v58, v59
	v_min_f32_e32 v59, v64, v246
	v_exp_f32_e32 v61, v61
	v_exp_f32_e32 v59, v59
	v_add_f32_e32 v62, 1.0, v62
	v_add_f32_e32 v60, 1.0, v60
	v_add_f32_e32 v61, 1.0, v61
	v_add_f32_e32 v59, 1.0, v59
	v_rcp_f32_e32 v59, v59
	v_rcp_f32_e32 v62, v62
	v_rcp_f32_e32 v60, v60
	v_rcp_f32_e32 v61, v61
	v_pk_mul_f32 v[54:55], v[54:55], v[66:67] op_sel_hi:[1,0]
	v_cvt_pk_bf16_f32 v59, v59, v62
	v_min_f32_e32 v62, v69, v246
	v_cvt_pk_bf16_f32 v60, v60, v61
	v_min_f32_e32 v61, v68, v246
	v_exp_f32_e32 v62, v62
	v_exp_f32_e32 v61, v61
	v_pk_mul_f32 v[56:57], v[56:57], v[66:67] op_sel_hi:[1,0]
	v_add_f32_e32 v62, 1.0, v62
	v_add_f32_e32 v61, 1.0, v61
	v_rcp_f32_e32 v61, v61
	v_rcp_f32_e32 v62, v62
	s_nop 0
	v_cvt_pk_bf16_f32 v61, v61, v62
	global_store_dwordx4 v[90:91], v[58:61], off
	s_nop 1
	v_pk_mul_f32 v[58:59], v[52:53], v[66:67] op_sel_hi:[1,0]
	v_pk_mul_f32 v[52:53], v[50:51], v[66:67] op_sel_hi:[1,0]
	v_min_f32_e32 v50, v54, v246
	v_min_f32_e32 v51, v55, v246
	v_min_f32_e32 v54, v57, v246
	v_exp_f32_e32 v50, v50
	v_exp_f32_e32 v51, v51
	v_min_f32_e32 v52, v52, v246
	v_min_f32_e32 v53, v53, v246
	v_add_f32_e32 v50, 1.0, v50
	v_add_f32_e32 v51, 1.0, v51
	v_rcp_f32_e32 v50, v50
	v_rcp_f32_e32 v51, v51
	v_exp_f32_e32 v54, v54
	v_exp_f32_e32 v52, v52
	v_exp_f32_e32 v53, v53
	v_cvt_pk_bf16_f32 v50, v50, v51
	v_min_f32_e32 v51, v56, v246
	v_add_f32_e32 v54, 1.0, v54
	v_exp_f32_e32 v51, v51
	v_add_f32_e32 v52, 1.0, v52
	v_add_f32_e32 v53, 1.0, v53
	v_rcp_f32_e32 v54, v54
	v_add_f32_e32 v51, 1.0, v51
	v_rcp_f32_e32 v51, v51
	v_rcp_f32_e32 v52, v52
	v_rcp_f32_e32 v53, v53
	v_cvt_pk_bf16_f32 v51, v51, v54
	v_min_f32_e32 v54, v59, v246
	v_cvt_pk_bf16_f32 v52, v52, v53
	v_min_f32_e32 v53, v58, v246
	v_exp_f32_e32 v54, v54
	v_exp_f32_e32 v53, v53
	v_add_f32_e32 v54, 1.0, v54
	v_add_f32_e32 v53, 1.0, v53
	v_rcp_f32_e32 v53, v53
	v_rcp_f32_e32 v54, v54
	s_nop 0
	v_cvt_pk_bf16_f32 v53, v53, v54
	global_store_dwordx4 v[90:91], v[50:53], off offset:1024
	s_nop 1
	v_mul_f32_e32 v50, 0xbfb8aa3b, v142
	v_pk_mul_f32 v[46:47], v[46:47], v[50:51] op_sel_hi:[1,0]
	v_pk_mul_f32 v[52:53], v[44:45], v[50:51] op_sel_hi:[1,0]
	v_pk_mul_f32 v[44:45], v[42:43], v[50:51] op_sel_hi:[1,0]
	v_min_f32_e32 v42, v46, v246
	v_min_f32_e32 v43, v47, v246
	v_pk_mul_f32 v[48:49], v[48:49], v[50:51] op_sel_hi:[1,0]
	v_exp_f32_e32 v42, v42
	v_exp_f32_e32 v43, v43
	v_min_f32_e32 v46, v49, v246
	v_min_f32_e32 v44, v44, v246
	v_add_f32_e32 v42, 1.0, v42
	v_add_f32_e32 v43, 1.0, v43
	v_rcp_f32_e32 v42, v42
	v_rcp_f32_e32 v43, v43
	v_min_f32_e32 v45, v45, v246
	v_exp_f32_e32 v46, v46
	v_exp_f32_e32 v44, v44
	v_cvt_pk_bf16_f32 v42, v42, v43
	v_min_f32_e32 v43, v48, v246
	v_exp_f32_e32 v45, v45
	v_exp_f32_e32 v43, v43
	v_add_f32_e32 v46, 1.0, v46
	v_add_f32_e32 v44, 1.0, v44
	v_add_f32_e32 v45, 1.0, v45
	v_add_f32_e32 v43, 1.0, v43
	v_rcp_f32_e32 v43, v43
	v_rcp_f32_e32 v46, v46
	v_rcp_f32_e32 v44, v44
	v_rcp_f32_e32 v45, v45
	v_pk_mul_f32 v[38:39], v[38:39], v[50:51] op_sel_hi:[1,0]
	v_cvt_pk_bf16_f32 v43, v43, v46
	v_min_f32_e32 v46, v53, v246
	v_cvt_pk_bf16_f32 v44, v44, v45
	v_min_f32_e32 v45, v52, v246
	v_exp_f32_e32 v46, v46
	v_exp_f32_e32 v45, v45
	v_pk_mul_f32 v[40:41], v[40:41], v[50:51] op_sel_hi:[1,0]
	v_add_f32_e32 v46, 1.0, v46
	v_add_f32_e32 v45, 1.0, v45
	v_rcp_f32_e32 v45, v45
	v_rcp_f32_e32 v46, v46
	s_nop 0
	v_cvt_pk_bf16_f32 v45, v45, v46
	global_store_dwordx4 v[90:91], v[42:45], off offset:2048
	s_nop 1
	v_pk_mul_f32 v[42:43], v[36:37], v[50:51] op_sel_hi:[1,0]
	v_pk_mul_f32 v[36:37], v[34:35], v[50:51] op_sel_hi:[1,0]
	v_min_f32_e32 v34, v38, v246
	v_min_f32_e32 v35, v39, v246
	v_min_f32_e32 v38, v41, v246
	v_exp_f32_e32 v34, v34
	v_exp_f32_e32 v35, v35
; __device__ __forceinline__ unsigned pk2(float lo, float hi) { f32x2 v = {lo, hi}; bf16x2_t b = __builtin_convertvector(v, bf16x2_t); return __builtin_bit_cast(unsigned, b); }
; #define SG_(t) __builtin_amdgcn_rcpf(1.f + __builtin_amdgcn_exp2f(min2f(t, 19.931568f)))
;     __device__ __forceinline__ void operator()(AccT& acc, const Unit& u, int wr, int wc, int fr, int fq, LAS unsigned char*) const {
;     ...
;             for (int m = 0; m < 4; ++m) {
;                 const float rs = rsa[ai][m] * -LOG2E;
;     ...
; #pragma unroll
;                 for (int bj = 0; bj < 2; ++bj) { const f32x4 v0 = acc[ai][bj][m][0] * rs, v1 = acc[ai][bj][m][1] * rs; u32x4 w;
;                     w.x = pk2(SG_(v0.x), SG_(v0.y)); w.y = pk2(SG_(v0.z), SG_(v0.w)); w.z = pk2(SG_(v1.x), SG_(v1.y)); w.w = pk2(SG_(v1.z), SG_(v1.w));
;     ...
;                     *(u32x4*)(gates + ((tb + (ai * 4 + m) * 2 + bj) * 64 + lane) * 8) = w; }
;             }
	v_min_f32_e32 v36, v36, v246
	v_min_f32_e32 v37, v37, v246
	v_add_f32_e32 v34, 1.0, v34
	v_add_f32_e32 v35, 1.0, v35
	v_rcp_f32_e32 v34, v34
	v_rcp_f32_e32 v35, v35
	v_exp_f32_e32 v38, v38
	v_exp_f32_e32 v36, v36
	v_exp_f32_e32 v37, v37
	v_cvt_pk_bf16_f32 v34, v34, v35
	v_min_f32_e32 v35, v40, v246
	v_add_f32_e32 v38, 1.0, v38
	v_exp_f32_e32 v35, v35
	v_add_f32_e32 v36, 1.0, v36
	v_add_f32_e32 v37, 1.0, v37
	v_rcp_f32_e32 v38, v38
	v_add_f32_e32 v35, 1.0, v35
	v_rcp_f32_e32 v35, v35
	v_rcp_f32_e32 v36, v36
	v_rcp_f32_e32 v37, v37
	v_cvt_pk_bf16_f32 v35, v35, v38
	v_min_f32_e32 v38, v43, v246
	v_cvt_pk_bf16_f32 v36, v36, v37
	v_min_f32_e32 v37, v42, v246
	v_exp_f32_e32 v38, v38
	v_exp_f32_e32 v37, v37
	v_add_f32_e32 v38, 1.0, v38
	v_add_f32_e32 v37, 1.0, v37
	v_rcp_f32_e32 v37, v37
	v_rcp_f32_e32 v38, v38
	s_nop 0
	v_cvt_pk_bf16_f32 v37, v37, v38
	global_store_dwordx4 v[90:91], v[34:37], off offset:3072
	s_nop 1
	v_mul_f32_e32 v34, 0xbfb8aa3b, v141
	v_pk_mul_f32 v[30:31], v[30:31], v[34:35] op_sel_hi:[1,0]
	v_pk_mul_f32 v[36:37], v[28:29], v[34:35] op_sel_hi:[1,0]
	v_min_f32_e32 v28, v30, v246
	v_min_f32_e32 v29, v31, v246
	v_pk_mul_f32 v[26:27], v[26:27], v[34:35] op_sel_hi:[1,0]
	v_exp_f32_e32 v28, v28
	v_exp_f32_e32 v29, v29
	v_pk_mul_f32 v[32:33], v[32:33], v[34:35] op_sel_hi:[1,0]
	v_min_f32_e32 v26, v26, v246
	v_add_f32_e32 v28, 1.0, v28
	v_add_f32_e32 v29, 1.0, v29
	v_rcp_f32_e32 v28, v28
	v_rcp_f32_e32 v29, v29
	v_min_f32_e32 v30, v33, v246
	v_min_f32_e32 v27, v27, v246
	v_exp_f32_e32 v26, v26
	v_cvt_pk_bf16_f32 v28, v28, v29
	v_min_f32_e32 v29, v32, v246
	v_exp_f32_e32 v30, v30
	v_exp_f32_e32 v29, v29
	v_exp_f32_e32 v27, v27
	v_add_f32_e32 v26, 1.0, v26
	v_add_f32_e32 v30, 1.0, v30
	v_add_f32_e32 v29, 1.0, v29
	v_add_f32_e32 v27, 1.0, v27
	v_rcp_f32_e32 v29, v29
	v_rcp_f32_e32 v30, v30
	v_rcp_f32_e32 v26, v26
	v_rcp_f32_e32 v27, v27
	v_pk_mul_f32 v[22:23], v[22:23], v[34:35] op_sel_hi:[1,0]
	v_cvt_pk_bf16_f32 v29, v29, v30
	v_pk_mul_f32 v[24:25], v[24:25], v[34:35] op_sel_hi:[1,0]
	v_cvt_pk_bf16_f32 v30, v26, v27
	v_min_f32_e32 v26, v36, v246
	v_min_f32_e32 v27, v37, v246
	v_exp_f32_e32 v26, v26
	v_exp_f32_e32 v27, v27
	v_add_f32_e32 v26, 1.0, v26
	v_add_f32_e32 v27, 1.0, v27
	v_rcp_f32_e32 v26, v26
	v_rcp_f32_e32 v27, v27
	s_nop 0
	v_cvt_pk_bf16_f32 v31, v26, v27
	v_add_co_u32_e32 v26, vcc, s0, v122
	s_mov_b64 s[0:1], -1
	s_nop 0
	v_addc_co_u32_e32 v27, vcc, 0, v123, vcc
	global_store_dwordx4 v[26:27], v[28:31], off
	s_andn2_b64 vcc, exec, s[38:39]
	s_nop 0
	v_pk_mul_f32 v[28:29], v[20:21], v[34:35] op_sel_hi:[1,0]
	v_pk_mul_f32 v[20:21], v[18:19], v[34:35] op_sel_hi:[1,0]
	v_min_f32_e32 v18, v22, v246
	v_min_f32_e32 v19, v23, v246
	v_min_f32_e32 v22, v25, v246
	v_exp_f32_e32 v18, v18
	v_exp_f32_e32 v19, v19
	v_min_f32_e32 v20, v20, v246
	v_min_f32_e32 v21, v21, v246
	v_add_f32_e32 v18, 1.0, v18
	v_add_f32_e32 v19, 1.0, v19
	v_rcp_f32_e32 v18, v18
	v_rcp_f32_e32 v19, v19
	v_exp_f32_e32 v22, v22
	v_exp_f32_e32 v20, v20
	v_exp_f32_e32 v21, v21
	v_cvt_pk_bf16_f32 v18, v18, v19
	v_min_f32_e32 v19, v24, v246
	v_add_f32_e32 v22, 1.0, v22
	v_exp_f32_e32 v19, v19
	v_add_f32_e32 v20, 1.0, v20
	v_add_f32_e32 v21, 1.0, v21
	v_rcp_f32_e32 v22, v22
	v_add_f32_e32 v19, 1.0, v19
	v_rcp_f32_e32 v19, v19
	v_rcp_f32_e32 v20, v20
	v_rcp_f32_e32 v21, v21
	v_cvt_pk_bf16_f32 v19, v19, v22
	v_min_f32_e32 v22, v29, v246
	v_cvt_pk_bf16_f32 v20, v20, v21
	v_min_f32_e32 v21, v28, v246
	v_exp_f32_e32 v22, v22
	v_exp_f32_e32 v21, v21
	v_add_f32_e32 v22, 1.0, v22
	v_add_f32_e32 v21, 1.0, v21
	v_rcp_f32_e32 v21, v21
	v_rcp_f32_e32 v22, v22
	s_nop 0
	v_cvt_pk_bf16_f32 v21, v21, v22
	global_store_dwordx4 v[26:27], v[18:21], off offset:1024
	s_nop 1
	v_mul_f32_e32 v18, 0xbfb8aa3b, v140
	v_pk_mul_f32 v[14:15], v[14:15], v[18:19] op_sel_hi:[1,0]
	v_pk_mul_f32 v[20:21], v[12:13], v[18:19] op_sel_hi:[1,0]
	v_pk_mul_f32 v[12:13], v[10:11], v[18:19] op_sel_hi:[1,0]
	v_min_f32_e32 v10, v14, v246
	v_min_f32_e32 v11, v15, v246
	v_pk_mul_f32 v[16:17], v[16:17], v[18:19] op_sel_hi:[1,0]
	v_exp_f32_e32 v10, v10
	v_exp_f32_e32 v11, v11
	v_min_f32_e32 v14, v17, v246
	v_min_f32_e32 v12, v12, v246
	v_add_f32_e32 v10, 1.0, v10
	v_add_f32_e32 v11, 1.0, v11
	v_rcp_f32_e32 v10, v10
	v_rcp_f32_e32 v11, v11
	v_min_f32_e32 v13, v13, v246
	v_exp_f32_e32 v14, v14
	v_exp_f32_e32 v12, v12
	v_cvt_pk_bf16_f32 v10, v10, v11
	v_min_f32_e32 v11, v16, v246
	v_exp_f32_e32 v13, v13
	v_exp_f32_e32 v11, v11
	v_add_f32_e32 v14, 1.0, v14
	v_add_f32_e32 v12, 1.0, v12
	v_add_f32_e32 v13, 1.0, v13
	v_add_f32_e32 v11, 1.0, v11
	v_rcp_f32_e32 v11, v11
	v_rcp_f32_e32 v14, v14
	v_rcp_f32_e32 v12, v12
	v_rcp_f32_e32 v13, v13
	v_pk_mul_f32 v[6:7], v[6:7], v[18:19] op_sel_hi:[1,0]
	v_cvt_pk_bf16_f32 v11, v11, v14
	v_min_f32_e32 v14, v21, v246
	v_cvt_pk_bf16_f32 v12, v12, v13
	v_min_f32_e32 v13, v20, v246
	v_exp_f32_e32 v14, v14
	v_exp_f32_e32 v13, v13
	v_pk_mul_f32 v[8:9], v[8:9], v[18:19] op_sel_hi:[1,0]
	v_add_f32_e32 v14, 1.0, v14
	v_add_f32_e32 v13, 1.0, v13
	v_rcp_f32_e32 v13, v13
	v_rcp_f32_e32 v14, v14
	s_nop 0
	v_cvt_pk_bf16_f32 v13, v13, v14
	global_store_dwordx4 v[26:27], v[10:13], off offset:2048
	s_nop 1
	v_pk_mul_f32 v[10:11], v[4:5], v[18:19] op_sel_hi:[1,0]
	v_pk_mul_f32 v[4:5], v[2:3], v[18:19] op_sel_hi:[1,0]
	v_min_f32_e32 v2, v6, v246
	v_min_f32_e32 v3, v7, v246
	v_min_f32_e32 v6, v9, v246
	v_exp_f32_e32 v2, v2
	v_exp_f32_e32 v3, v3
	v_min_f32_e32 v4, v4, v246
	v_min_f32_e32 v5, v5, v246
	v_add_f32_e32 v2, 1.0, v2
	v_add_f32_e32 v3, 1.0, v3
	v_rcp_f32_e32 v2, v2
	v_rcp_f32_e32 v3, v3
	v_exp_f32_e32 v6, v6
	v_exp_f32_e32 v4, v4
	v_exp_f32_e32 v5, v5
	v_cvt_pk_bf16_f32 v2, v2, v3
	v_min_f32_e32 v3, v8, v246
	v_add_f32_e32 v6, 1.0, v6
	v_exp_f32_e32 v3, v3
	v_add_f32_e32 v4, 1.0, v4
	v_add_f32_e32 v5, 1.0, v5
	v_rcp_f32_e32 v6, v6
	v_add_f32_e32 v3, 1.0, v3
	v_rcp_f32_e32 v3, v3
	v_rcp_f32_e32 v4, v4
	v_rcp_f32_e32 v5, v5
	v_cvt_pk_bf16_f32 v3, v3, v6
	v_min_f32_e32 v6, v11, v246
	v_cvt_pk_bf16_f32 v4, v4, v5
	v_min_f32_e32 v5, v10, v246
	v_exp_f32_e32 v6, v6
	v_exp_f32_e32 v5, v5
	v_add_f32_e32 v6, 1.0, v6
	v_add_f32_e32 v5, 1.0, v5
	v_rcp_f32_e32 v5, v5
	v_rcp_f32_e32 v6, v6
	s_nop 0
	v_cvt_pk_bf16_f32 v5, v5, v6
	global_store_dwordx4 v[26:27], v[2:5], off offset:3072
	s_cbranch_vccnz .LBB0_328
	s_andn2_b64 vcc, exec, s[6:7]
	s_cbranch_vccnz .LBB0_327
	s_barrier
	s_branch .LBB0_327
